# v18 + branch-GEMM gate epilogue: vmcnt counts made path-dependent (8/6 when the MIX read-modify-write loads exist) so an iteration no longer waits for the previous iteration's stores
# baseline (speedup 1.0000x reference)
; __device__ __forceinline__ unsigned cvt_pk_bf16(float lo, float hi) { unsigned r; asm volatile("v_cvt_pk_bf16_f32 %0, %1, %2" : "=v"(r) : "v"(lo), "v"(hi)); return r; }
; __device__ __forceinline__ float bf_lo(unsigned w) { return __uint_as_float(w << 16); }
; __device__ __forceinline__ float bf_hi(unsigned w) { return __uint_as_float(w & 0xffff0000u); }
; #define EG_LOAD(slot, it) do { const size_t row_ = (size_t)(row0 + ((it) >> 2) * HALF + ((it) & 3) * 16); _Pragma("unroll") for (int bj = 0; bj < 2; ++bj) { \
;             g[slot][bj] = gld((const u32x4*)(G + row_ * ldg + col0 + bj * HALF)); o[slot][bj] = (u32x4){0u, 0u, 0u, 0u}; if (!first) o[slot][bj] = gld((const u32x4*)(MIX + row_ * ldm + col0 + bj * HALF)); } } while (0)
;     __device__ __forceinline__ void operator()(const f32x4 (&acc)[2][2][4][2], const Unit& u, int wr, int wc, int fr, int fq) const {
;     ...
;         for (int it = 0; it < 8; ++it) { const int ai = it >> 2, m = it & 3, sl = it & 1; const size_t row = (size_t)(row0 + ai * HALF + m * 16);
;             if (it + 1 < 8) EG_LOAD(sl ^ 1, it + 1);
; #pragma unroll
;             for (int bj = 0; bj < 2; ++bj) { const u32x4 gg = g[sl][bj], oo = o[sl][bj]; const f32x4 v0 = acc[ai][bj][m][0], v1 = acc[ai][bj][m][1]; u32x4 w;
;                 w.x = cvt_pk_bf16(bf_lo(oo.x) + bf_lo(gg.x) * v0[0], bf_hi(oo.x) + bf_hi(gg.x) * v0[1]);
;                 w.y = cvt_pk_bf16(bf_lo(oo.y) + bf_lo(gg.y) * v0[2], bf_hi(oo.y) + bf_hi(gg.y) * v0[3]);
;                 w.z = cvt_pk_bf16(bf_lo(oo.z) + bf_lo(gg.z) * v1[0], bf_hi(oo.z) + bf_hi(gg.z) * v1[1]);
;                 w.w = cvt_pk_bf16(bf_lo(oo.w) + bf_lo(gg.w) * v1[2], bf_hi(oo.w) + bf_hi(gg.w) * v1[3]);
;                 gst((u32x4*)(MIX + row * ldm + col0 + bj * HALF), w); }
.LBB0_1383:
	s_cbranch_vccnz .Lmy_gf_9
	s_waitcnt vmcnt(8)
	s_branch .Lmy_gd_9

; __device__ __forceinline__ unsigned cvt_pk_bf16(float lo, float hi) { unsigned r; asm volatile("v_cvt_pk_bf16_f32 %0, %1, %2" : "=v"(r) : "v"(lo), "v"(hi)); return r; }
; __device__ __forceinline__ float bf_lo(unsigned w) { return __uint_as_float(w << 16); }
; __device__ __forceinline__ float bf_hi(unsigned w) { return __uint_as_float(w & 0xffff0000u); }
; #define EG_LOAD(slot, it) do { const size_t row_ = (size_t)(row0 + ((it) >> 2) * HALF + ((it) & 3) * 16); _Pragma("unroll") for (int bj = 0; bj < 2; ++bj) { \
;             g[slot][bj] = gld((const u32x4*)(G + row_ * ldg + col0 + bj * HALF)); o[slot][bj] = (u32x4){0u, 0u, 0u, 0u}; if (!first) o[slot][bj] = gld((const u32x4*)(MIX + row_ * ldm + col0 + bj * HALF)); } } while (0)
;     __device__ __forceinline__ void operator()(const f32x4 (&acc)[2][2][4][2], const Unit& u, int wr, int wc, int fr, int fq) const {
;     ...
;         EG_LOAD(0, 0);
; #pragma unroll
;         for (int it = 0; it < 8; ++it) { const int ai = it >> 2, m = it & 3, sl = it & 1; const size_t row = (size_t)(row0 + ai * HALF + m * 16);
;             if (it + 1 < 8) EG_LOAD(sl ^ 1, it + 1);
; #pragma unroll
;             for (int bj = 0; bj < 2; ++bj) { const u32x4 gg = g[sl][bj], oo = o[sl][bj]; const f32x4 v0 = acc[ai][bj][m][0], v1 = acc[ai][bj][m][1]; u32x4 w;
;                 w.x = cvt_pk_bf16(bf_lo(oo.x) + bf_lo(gg.x) * v0[0], bf_hi(oo.x) + bf_hi(gg.x) * v0[1]);
;                 w.y = cvt_pk_bf16(bf_lo(oo.y) + bf_lo(gg.y) * v0[2], bf_hi(oo.y) + bf_hi(gg.y) * v0[3]);
;                 w.z = cvt_pk_bf16(bf_lo(oo.z) + bf_lo(gg.z) * v1[0], bf_hi(oo.z) + bf_hi(gg.z) * v1[1]);
;                 w.w = cvt_pk_bf16(bf_lo(oo.w) + bf_lo(gg.w) * v1[2], bf_hi(oo.w) + bf_hi(gg.w) * v1[3]);
;                 gst((u32x4*)(MIX + row * ldm + col0 + bj * HALF), w); }
.Lmy_gd_9:
	v_lshlrev_b32_e32 v132, 16, v126
	v_lshlrev_b32_e32 v133, 16, v122
	v_fmac_f32_e32 v132, v94, v133
	v_and_b32_e32 v94, 0xffff0000, v126
	v_and_b32_e32 v122, 0xffff0000, v122
	v_fmac_f32_e32 v94, v95, v122
	v_lshlrev_b32_e32 v95, 16, v127
	v_lshlrev_b32_e32 v122, 16, v123
	v_fmac_f32_e32 v95, v96, v122
	v_and_b32_e32 v96, 0xffff0000, v127
	v_and_b32_e32 v122, 0xffff0000, v123
	v_fmac_f32_e32 v96, v97, v122
	v_cvt_pk_bf16_f32 v94, v132, v94
	v_cvt_pk_bf16_f32 v95, v95, v96
	v_lshlrev_b32_e32 v96, 16, v128
	v_lshlrev_b32_e32 v97, 16, v124
	v_fmac_f32_e32 v96, v90, v97
	v_and_b32_e32 v90, 0xffff0000, v128
	v_and_b32_e32 v97, 0xffff0000, v124
	v_fmac_f32_e32 v90, v91, v97
	v_cvt_pk_bf16_f32 v96, v96, v90
	v_lshlrev_b32_e32 v90, 16, v129
	v_lshlrev_b32_e32 v91, 16, v125
	v_fmac_f32_e32 v90, v92, v91
	v_and_b32_e32 v91, 0xffff0000, v129
	v_and_b32_e32 v92, 0xffff0000, v125
	v_fmac_f32_e32 v91, v93, v92
	v_cvt_pk_bf16_f32 v97, v90, v91
	s_cbranch_vccnz .Lmy_gf_8
	s_waitcnt vmcnt(6)
	s_branch .Lmy_gd_8
.Lmy_gf_8:
	s_waitcnt vmcnt(4)
.Lmy_gd_8:
	v_lshlrev_b32_e32 v90, 16, v114
	v_lshlrev_b32_e32 v91, 16, v118
	v_fmac_f32_e32 v90, v86, v91
	v_and_b32_e32 v86, 0xffff0000, v114
	v_and_b32_e32 v91, 0xffff0000, v118
	v_fmac_f32_e32 v86, v87, v91
	global_store_dwordx4 v[146:147], v[94:97], off
	v_cvt_pk_bf16_f32 v86, v90, v86
	v_lshlrev_b32_e32 v87, 16, v115
	v_lshlrev_b32_e32 v90, 16, v119
	v_fmac_f32_e32 v87, v88, v90
	v_and_b32_e32 v88, 0xffff0000, v115
	v_and_b32_e32 v90, 0xffff0000, v119
	v_fmac_f32_e32 v88, v89, v90
	v_cvt_pk_bf16_f32 v87, v87, v88
	v_lshlrev_b32_e32 v88, 16, v116
	v_lshlrev_b32_e32 v89, 16, v120
	v_fmac_f32_e32 v88, v82, v89
	v_and_b32_e32 v82, 0xffff0000, v116
	v_and_b32_e32 v89, 0xffff0000, v120
	v_fmac_f32_e32 v82, v83, v89
	v_cvt_pk_bf16_f32 v88, v88, v82
	v_lshlrev_b32_e32 v82, 16, v117
	v_lshlrev_b32_e32 v83, 16, v121
	v_fmac_f32_e32 v82, v84, v83
	v_and_b32_e32 v83, 0xffff0000, v117
	v_and_b32_e32 v84, 0xffff0000, v121
	v_fmac_f32_e32 v83, v85, v84
	v_cvt_pk_bf16_f32 v89, v82, v83
	v_add_u32_e32 v114, 0x80, v174
	v_mov_b64_e32 v[82:83], s[18:19]
	global_store_dwordx4 v[146:147], v[86:89], off offset:256
	v_mad_i64_i32 v[82:83], s[50:51], v114, s81, v[82:83]
	v_lshl_add_u64 v[84:85], v[82:83], 0, v[172:173]
	global_load_dwordx4 v[90:93], v[84:85], off
	v_ashrrev_i32_e32 v115, 31, v114
	v_lshlrev_b64 v[82:83], 11, v[114:115]
	v_lshl_add_u64 v[82:83], s[12:13], 0, v[82:83]
	v_lshl_add_u64 v[116:117], v[82:83], 0, v[172:173]
	v_mov_b32_e32 v82, 0
	s_and_b64 vcc, exec, s[42:43]
	v_mov_b32_e32 v94, 0
	v_mov_b32_e32 v95, 0
	v_mov_b32_e32 v96, 0
	v_mov_b32_e32 v97, 0
	s_cbranch_vccnz .LBB0_1385
	global_load_dwordx4 v[94:97], v[116:117], off

; __device__ __forceinline__ unsigned cvt_pk_bf16(float lo, float hi) { unsigned r; asm volatile("v_cvt_pk_bf16_f32 %0, %1, %2" : "=v"(r) : "v"(lo), "v"(hi)); return r; }
; __device__ __forceinline__ float bf_lo(unsigned w) { return __uint_as_float(w << 16); }
; __device__ __forceinline__ float bf_hi(unsigned w) { return __uint_as_float(w & 0xffff0000u); }
; #define EG_LOAD(slot, it) do { const size_t row_ = (size_t)(row0 + ((it) >> 2) * HALF + ((it) & 3) * 16); _Pragma("unroll") for (int bj = 0; bj < 2; ++bj) { \
;             g[slot][bj] = gld((const u32x4*)(G + row_ * ldg + col0 + bj * HALF)); o[slot][bj] = (u32x4){0u, 0u, 0u, 0u}; if (!first) o[slot][bj] = gld((const u32x4*)(MIX + row_ * ldm + col0 + bj * HALF)); } } while (0)
;     __device__ __forceinline__ void operator()(const f32x4 (&acc)[2][2][4][2], const Unit& u, int wr, int wc, int fr, int fq) const {
;     ...
;         for (int it = 0; it < 8; ++it) { const int ai = it >> 2, m = it & 3, sl = it & 1; const size_t row = (size_t)(row0 + ai * HALF + m * 16);
;             if (it + 1 < 8) EG_LOAD(sl ^ 1, it + 1);
; #pragma unroll
;             for (int bj = 0; bj < 2; ++bj) { const u32x4 gg = g[sl][bj], oo = o[sl][bj]; const f32x4 v0 = acc[ai][bj][m][0], v1 = acc[ai][bj][m][1]; u32x4 w;
;                 w.x = cvt_pk_bf16(bf_lo(oo.x) + bf_lo(gg.x) * v0[0], bf_hi(oo.x) + bf_hi(gg.x) * v0[1]);
;                 w.y = cvt_pk_bf16(bf_lo(oo.y) + bf_lo(gg.y) * v0[2], bf_hi(oo.y) + bf_hi(gg.y) * v0[3]);
;                 w.z = cvt_pk_bf16(bf_lo(oo.z) + bf_lo(gg.z) * v1[0], bf_hi(oo.z) + bf_hi(gg.z) * v1[1]);
;                 w.w = cvt_pk_bf16(bf_lo(oo.w) + bf_lo(gg.w) * v1[2], bf_hi(oo.w) + bf_hi(gg.w) * v1[3]);
;                 gst((u32x4*)(MIX + row * ldm + col0 + bj * HALF), w); }
.Lmy_gd_7:
	v_lshlrev_b32_e32 v115, 16, v110
	v_lshlrev_b32_e32 v118, 16, v106
	v_fmac_f32_e32 v115, v78, v118
	v_and_b32_e32 v78, 0xffff0000, v110
	v_and_b32_e32 v106, 0xffff0000, v106
	v_fmac_f32_e32 v78, v79, v106
	v_lshlrev_b32_e32 v79, 16, v111
	v_lshlrev_b32_e32 v106, 16, v107
	v_fmac_f32_e32 v79, v80, v106
	v_and_b32_e32 v80, 0xffff0000, v111
	v_and_b32_e32 v106, 0xffff0000, v107
	v_fmac_f32_e32 v80, v81, v106
	v_cvt_pk_bf16_f32 v78, v115, v78
	v_cvt_pk_bf16_f32 v79, v79, v80
	v_lshlrev_b32_e32 v80, 16, v112
	v_lshlrev_b32_e32 v81, 16, v108
	v_fmac_f32_e32 v80, v74, v81
	v_and_b32_e32 v74, 0xffff0000, v112
	v_and_b32_e32 v81, 0xffff0000, v108
	v_fmac_f32_e32 v74, v75, v81
	v_cvt_pk_bf16_f32 v80, v80, v74
	v_lshlrev_b32_e32 v74, 16, v113
	v_lshlrev_b32_e32 v75, 16, v109
	v_fmac_f32_e32 v74, v76, v75
	v_and_b32_e32 v75, 0xffff0000, v113
	v_and_b32_e32 v76, 0xffff0000, v109
	v_fmac_f32_e32 v75, v77, v76
	v_cvt_pk_bf16_f32 v81, v74, v75
	s_cbranch_vccnz .Lmy_gf_6
	s_waitcnt vmcnt(6)
	s_branch .Lmy_gd_6

; __device__ __forceinline__ unsigned cvt_pk_bf16(float lo, float hi) { unsigned r; asm volatile("v_cvt_pk_bf16_f32 %0, %1, %2" : "=v"(r) : "v"(lo), "v"(hi)); return r; }
; __device__ __forceinline__ float bf_lo(unsigned w) { return __uint_as_float(w << 16); }
; __device__ __forceinline__ float bf_hi(unsigned w) { return __uint_as_float(w & 0xffff0000u); }
; #define EG_LOAD(slot, it) do { const size_t row_ = (size_t)(row0 + ((it) >> 2) * HALF + ((it) & 3) * 16); _Pragma("unroll") for (int bj = 0; bj < 2; ++bj) { \
;             g[slot][bj] = gld((const u32x4*)(G + row_ * ldg + col0 + bj * HALF)); o[slot][bj] = (u32x4){0u, 0u, 0u, 0u}; if (!first) o[slot][bj] = gld((const u32x4*)(MIX + row_ * ldm + col0 + bj * HALF)); } } while (0)
;     __device__ __forceinline__ void operator()(const f32x4 (&acc)[2][2][4][2], const Unit& u, int wr, int wc, int fr, int fq) const {
;     ...
;         EG_LOAD(0, 0);
; #pragma unroll
;         for (int it = 0; it < 8; ++it) { const int ai = it >> 2, m = it & 3, sl = it & 1; const size_t row = (size_t)(row0 + ai * HALF + m * 16);
;             if (it + 1 < 8) EG_LOAD(sl ^ 1, it + 1);
; #pragma unroll
;             for (int bj = 0; bj < 2; ++bj) { const u32x4 gg = g[sl][bj], oo = o[sl][bj]; const f32x4 v0 = acc[ai][bj][m][0], v1 = acc[ai][bj][m][1]; u32x4 w;
;                 w.x = cvt_pk_bf16(bf_lo(oo.x) + bf_lo(gg.x) * v0[0], bf_hi(oo.x) + bf_hi(gg.x) * v0[1]);
;                 w.y = cvt_pk_bf16(bf_lo(oo.y) + bf_lo(gg.y) * v0[2], bf_hi(oo.y) + bf_hi(gg.y) * v0[3]);
;                 w.z = cvt_pk_bf16(bf_lo(oo.z) + bf_lo(gg.z) * v1[0], bf_hi(oo.z) + bf_hi(gg.z) * v1[1]);
;                 w.w = cvt_pk_bf16(bf_lo(oo.w) + bf_lo(gg.w) * v1[2], bf_hi(oo.w) + bf_hi(gg.w) * v1[3]);
;                 gst((u32x4*)(MIX + row * ldm + col0 + bj * HALF), w); }
.Lmy_gd_6:
	v_lshlrev_b32_e32 v74, 16, v98
	v_lshlrev_b32_e32 v75, 16, v102
	v_fmac_f32_e32 v74, v70, v75
	v_and_b32_e32 v70, 0xffff0000, v98
	v_and_b32_e32 v75, 0xffff0000, v102
	v_fmac_f32_e32 v70, v71, v75
	global_store_dwordx4 v[130:131], v[78:81], off
	v_cvt_pk_bf16_f32 v70, v74, v70
	v_lshlrev_b32_e32 v71, 16, v99
	v_lshlrev_b32_e32 v74, 16, v103
	v_fmac_f32_e32 v71, v72, v74
	v_and_b32_e32 v72, 0xffff0000, v99
	v_and_b32_e32 v74, 0xffff0000, v103
	v_fmac_f32_e32 v72, v73, v74
	v_cvt_pk_bf16_f32 v71, v71, v72
	v_lshlrev_b32_e32 v72, 16, v100
	v_lshlrev_b32_e32 v73, 16, v104
	v_fmac_f32_e32 v72, v66, v73
	v_and_b32_e32 v66, 0xffff0000, v100
	v_and_b32_e32 v73, 0xffff0000, v104
	v_fmac_f32_e32 v66, v67, v73
	v_cvt_pk_bf16_f32 v72, v72, v66
	v_lshlrev_b32_e32 v66, 16, v101
	v_lshlrev_b32_e32 v67, 16, v105
	v_fmac_f32_e32 v66, v68, v67
	v_and_b32_e32 v67, 0xffff0000, v101
	v_and_b32_e32 v68, 0xffff0000, v105
	v_fmac_f32_e32 v67, v69, v68
	v_cvt_pk_bf16_f32 v73, v66, v67
	v_or_b32_e32 v66, 16, v114
	v_mov_b64_e32 v[68:69], s[18:19]
	global_store_dwordx4 v[130:131], v[70:73], off offset:256
	v_mad_i64_i32 v[68:69], s[50:51], v66, s81, v[68:69]
	v_lshl_add_u64 v[68:69], v[68:69], 0, v[172:173]
	global_load_dwordx4 v[74:77], v[68:69], off
	v_ashrrev_i32_e32 v67, 31, v66
	v_lshlrev_b64 v[66:67], 11, v[66:67]
	v_lshl_add_u64 v[66:67], s[12:13], 0, v[66:67]
	v_lshl_add_u64 v[98:99], v[66:67], 0, v[172:173]
	v_mov_b32_e32 v66, 0
	s_and_b64 vcc, exec, s[42:43]
	v_mov_b32_e32 v78, 0
	v_mov_b32_e32 v79, 0
	v_mov_b32_e32 v80, 0
	v_mov_b32_e32 v81, 0
	s_cbranch_vccnz .LBB0_1389
	global_load_dwordx4 v[78:81], v[98:99], off

; __device__ __forceinline__ unsigned cvt_pk_bf16(float lo, float hi) { unsigned r; asm volatile("v_cvt_pk_bf16_f32 %0, %1, %2" : "=v"(r) : "v"(lo), "v"(hi)); return r; }
; __device__ __forceinline__ float bf_lo(unsigned w) { return __uint_as_float(w << 16); }
; __device__ __forceinline__ float bf_hi(unsigned w) { return __uint_as_float(w & 0xffff0000u); }
; #define EG_LOAD(slot, it) do { const size_t row_ = (size_t)(row0 + ((it) >> 2) * HALF + ((it) & 3) * 16); _Pragma("unroll") for (int bj = 0; bj < 2; ++bj) { \
;             g[slot][bj] = gld((const u32x4*)(G + row_ * ldg + col0 + bj * HALF)); o[slot][bj] = (u32x4){0u, 0u, 0u, 0u}; if (!first) o[slot][bj] = gld((const u32x4*)(MIX + row_ * ldm + col0 + bj * HALF)); } } while (0)
;     __device__ __forceinline__ void operator()(const f32x4 (&acc)[2][2][4][2], const Unit& u, int wr, int wc, int fr, int fq) const {
;     ...
;         for (int it = 0; it < 8; ++it) { const int ai = it >> 2, m = it & 3, sl = it & 1; const size_t row = (size_t)(row0 + ai * HALF + m * 16);
;             if (it + 1 < 8) EG_LOAD(sl ^ 1, it + 1);
; #pragma unroll
;             for (int bj = 0; bj < 2; ++bj) { const u32x4 gg = g[sl][bj], oo = o[sl][bj]; const f32x4 v0 = acc[ai][bj][m][0], v1 = acc[ai][bj][m][1]; u32x4 w;
;                 w.x = cvt_pk_bf16(bf_lo(oo.x) + bf_lo(gg.x) * v0[0], bf_hi(oo.x) + bf_hi(gg.x) * v0[1]);
;                 w.y = cvt_pk_bf16(bf_lo(oo.y) + bf_lo(gg.y) * v0[2], bf_hi(oo.y) + bf_hi(gg.y) * v0[3]);
;                 w.z = cvt_pk_bf16(bf_lo(oo.z) + bf_lo(gg.z) * v1[0], bf_hi(oo.z) + bf_hi(gg.z) * v1[1]);
;                 w.w = cvt_pk_bf16(bf_lo(oo.w) + bf_lo(gg.w) * v1[2], bf_hi(oo.w) + bf_hi(gg.w) * v1[3]);
;                 gst((u32x4*)(MIX + row * ldm + col0 + bj * HALF), w); }
.Lmy_gd_5:
	v_lshlrev_b32_e32 v100, 16, v94
	v_lshlrev_b32_e32 v101, 16, v90
	v_fmac_f32_e32 v100, v62, v101
	v_and_b32_e32 v62, 0xffff0000, v94
	v_and_b32_e32 v90, 0xffff0000, v90
	v_fmac_f32_e32 v62, v63, v90
	v_lshlrev_b32_e32 v63, 16, v95
	v_lshlrev_b32_e32 v90, 16, v91
	v_fmac_f32_e32 v63, v64, v90
	v_and_b32_e32 v64, 0xffff0000, v95
	v_and_b32_e32 v90, 0xffff0000, v91
	v_fmac_f32_e32 v64, v65, v90
	v_cvt_pk_bf16_f32 v62, v100, v62
	v_cvt_pk_bf16_f32 v63, v63, v64
	v_lshlrev_b32_e32 v64, 16, v96
	v_lshlrev_b32_e32 v65, 16, v92
	v_fmac_f32_e32 v64, v58, v65
	v_and_b32_e32 v58, 0xffff0000, v96
	v_and_b32_e32 v65, 0xffff0000, v92
	v_fmac_f32_e32 v58, v59, v65
	v_cvt_pk_bf16_f32 v64, v64, v58
	v_lshlrev_b32_e32 v58, 16, v97
	v_lshlrev_b32_e32 v59, 16, v93
	v_fmac_f32_e32 v58, v60, v59
	v_and_b32_e32 v59, 0xffff0000, v97
	v_and_b32_e32 v60, 0xffff0000, v93
	v_fmac_f32_e32 v59, v61, v60
	v_cvt_pk_bf16_f32 v65, v58, v59
	s_cbranch_vccnz .Lmy_gf_4
	s_waitcnt vmcnt(6)
	s_branch .Lmy_gd_4

; __device__ __forceinline__ unsigned cvt_pk_bf16(float lo, float hi) { unsigned r; asm volatile("v_cvt_pk_bf16_f32 %0, %1, %2" : "=v"(r) : "v"(lo), "v"(hi)); return r; }
; __device__ __forceinline__ float bf_lo(unsigned w) { return __uint_as_float(w << 16); }
; __device__ __forceinline__ float bf_hi(unsigned w) { return __uint_as_float(w & 0xffff0000u); }
; #define EG_LOAD(slot, it) do { const size_t row_ = (size_t)(row0 + ((it) >> 2) * HALF + ((it) & 3) * 16); _Pragma("unroll") for (int bj = 0; bj < 2; ++bj) { \
;             g[slot][bj] = gld((const u32x4*)(G + row_ * ldg + col0 + bj * HALF)); o[slot][bj] = (u32x4){0u, 0u, 0u, 0u}; if (!first) o[slot][bj] = gld((const u32x4*)(MIX + row_ * ldm + col0 + bj * HALF)); } } while (0)
;     __device__ __forceinline__ void operator()(const f32x4 (&acc)[2][2][4][2], const Unit& u, int wr, int wc, int fr, int fq) const {
;     ...
;         EG_LOAD(0, 0);
; #pragma unroll
;         for (int it = 0; it < 8; ++it) { const int ai = it >> 2, m = it & 3, sl = it & 1; const size_t row = (size_t)(row0 + ai * HALF + m * 16);
;             if (it + 1 < 8) EG_LOAD(sl ^ 1, it + 1);
; #pragma unroll
;             for (int bj = 0; bj < 2; ++bj) { const u32x4 gg = g[sl][bj], oo = o[sl][bj]; const f32x4 v0 = acc[ai][bj][m][0], v1 = acc[ai][bj][m][1]; u32x4 w;
;                 w.x = cvt_pk_bf16(bf_lo(oo.x) + bf_lo(gg.x) * v0[0], bf_hi(oo.x) + bf_hi(gg.x) * v0[1]);
;                 w.y = cvt_pk_bf16(bf_lo(oo.y) + bf_lo(gg.y) * v0[2], bf_hi(oo.y) + bf_hi(gg.y) * v0[3]);
;                 w.z = cvt_pk_bf16(bf_lo(oo.z) + bf_lo(gg.z) * v1[0], bf_hi(oo.z) + bf_hi(gg.z) * v1[1]);
;                 w.w = cvt_pk_bf16(bf_lo(oo.w) + bf_lo(gg.w) * v1[2], bf_hi(oo.w) + bf_hi(gg.w) * v1[3]);
;                 gst((u32x4*)(MIX + row * ldm + col0 + bj * HALF), w); }
.Lmy_gd_4:
	v_lshlrev_b32_e32 v58, 16, v82
	v_lshlrev_b32_e32 v59, 16, v86
	v_fmac_f32_e32 v58, v54, v59
	v_and_b32_e32 v54, 0xffff0000, v82
	v_and_b32_e32 v59, 0xffff0000, v86
	v_fmac_f32_e32 v54, v55, v59
	global_store_dwordx4 v[116:117], v[62:65], off
	v_cvt_pk_bf16_f32 v54, v58, v54
	v_lshlrev_b32_e32 v55, 16, v83
	v_lshlrev_b32_e32 v58, 16, v87
	v_fmac_f32_e32 v55, v56, v58
	v_and_b32_e32 v56, 0xffff0000, v83
	v_and_b32_e32 v58, 0xffff0000, v87
	v_fmac_f32_e32 v56, v57, v58
	v_cvt_pk_bf16_f32 v55, v55, v56
	v_lshlrev_b32_e32 v56, 16, v84
	v_lshlrev_b32_e32 v57, 16, v88
	v_fmac_f32_e32 v56, v50, v57
	v_and_b32_e32 v50, 0xffff0000, v84
	v_and_b32_e32 v57, 0xffff0000, v88
	v_fmac_f32_e32 v50, v51, v57
	v_cvt_pk_bf16_f32 v56, v56, v50
	v_lshlrev_b32_e32 v50, 16, v85
	v_lshlrev_b32_e32 v51, 16, v89
	v_fmac_f32_e32 v50, v52, v51
	v_and_b32_e32 v51, 0xffff0000, v85
	v_and_b32_e32 v52, 0xffff0000, v89
	v_fmac_f32_e32 v51, v53, v52
	v_cvt_pk_bf16_f32 v57, v50, v51
	v_or_b32_e32 v50, 32, v114
	v_mov_b64_e32 v[52:53], s[18:19]
	global_store_dwordx4 v[116:117], v[54:57], off offset:256
	v_mad_i64_i32 v[52:53], s[50:51], v50, s81, v[52:53]
	v_lshl_add_u64 v[52:53], v[52:53], 0, v[172:173]
	global_load_dwordx4 v[58:61], v[52:53], off
	v_ashrrev_i32_e32 v51, 31, v50
	v_lshlrev_b64 v[50:51], 11, v[50:51]
	v_lshl_add_u64 v[50:51], s[12:13], 0, v[50:51]
	v_lshl_add_u64 v[82:83], v[50:51], 0, v[172:173]
	v_mov_b32_e32 v50, 0
	s_and_b64 vcc, exec, s[42:43]
	v_mov_b32_e32 v62, 0
	v_mov_b32_e32 v63, 0
	v_mov_b32_e32 v64, 0
	v_mov_b32_e32 v65, 0
	s_cbranch_vccnz .LBB0_1393
	global_load_dwordx4 v[62:65], v[82:83], off

; __device__ __forceinline__ unsigned cvt_pk_bf16(float lo, float hi) { unsigned r; asm volatile("v_cvt_pk_bf16_f32 %0, %1, %2" : "=v"(r) : "v"(lo), "v"(hi)); return r; }
; __device__ __forceinline__ float bf_lo(unsigned w) { return __uint_as_float(w << 16); }
; __device__ __forceinline__ float bf_hi(unsigned w) { return __uint_as_float(w & 0xffff0000u); }
; #define EG_LOAD(slot, it) do { const size_t row_ = (size_t)(row0 + ((it) >> 2) * HALF + ((it) & 3) * 16); _Pragma("unroll") for (int bj = 0; bj < 2; ++bj) { \
;             g[slot][bj] = gld((const u32x4*)(G + row_ * ldg + col0 + bj * HALF)); o[slot][bj] = (u32x4){0u, 0u, 0u, 0u}; if (!first) o[slot][bj] = gld((const u32x4*)(MIX + row_ * ldm + col0 + bj * HALF)); } } while (0)
;     __device__ __forceinline__ void operator()(const f32x4 (&acc)[2][2][4][2], const Unit& u, int wr, int wc, int fr, int fq) const {
;     ...
;         for (int it = 0; it < 8; ++it) { const int ai = it >> 2, m = it & 3, sl = it & 1; const size_t row = (size_t)(row0 + ai * HALF + m * 16);
;             if (it + 1 < 8) EG_LOAD(sl ^ 1, it + 1);
; #pragma unroll
;             for (int bj = 0; bj < 2; ++bj) { const u32x4 gg = g[sl][bj], oo = o[sl][bj]; const f32x4 v0 = acc[ai][bj][m][0], v1 = acc[ai][bj][m][1]; u32x4 w;
;                 w.x = cvt_pk_bf16(bf_lo(oo.x) + bf_lo(gg.x) * v0[0], bf_hi(oo.x) + bf_hi(gg.x) * v0[1]);
;                 w.y = cvt_pk_bf16(bf_lo(oo.y) + bf_lo(gg.y) * v0[2], bf_hi(oo.y) + bf_hi(gg.y) * v0[3]);
;                 w.z = cvt_pk_bf16(bf_lo(oo.z) + bf_lo(gg.z) * v1[0], bf_hi(oo.z) + bf_hi(gg.z) * v1[1]);
;                 w.w = cvt_pk_bf16(bf_lo(oo.w) + bf_lo(gg.w) * v1[2], bf_hi(oo.w) + bf_hi(gg.w) * v1[3]);
;                 gst((u32x4*)(MIX + row * ldm + col0 + bj * HALF), w); }
.Lmy_gd_3:
	v_lshlrev_b32_e32 v84, 16, v78
	v_lshlrev_b32_e32 v85, 16, v74
	v_fmac_f32_e32 v84, v46, v85
	v_and_b32_e32 v46, 0xffff0000, v78
	v_and_b32_e32 v74, 0xffff0000, v74
	v_fmac_f32_e32 v46, v47, v74
	v_lshlrev_b32_e32 v47, 16, v79
	v_lshlrev_b32_e32 v74, 16, v75
	v_fmac_f32_e32 v47, v48, v74
	v_and_b32_e32 v48, 0xffff0000, v79
	v_and_b32_e32 v74, 0xffff0000, v75
	v_fmac_f32_e32 v48, v49, v74
	v_cvt_pk_bf16_f32 v46, v84, v46
	v_cvt_pk_bf16_f32 v47, v47, v48
	v_lshlrev_b32_e32 v48, 16, v80
	v_lshlrev_b32_e32 v49, 16, v76
	v_fmac_f32_e32 v48, v42, v49
	v_and_b32_e32 v42, 0xffff0000, v80
	v_and_b32_e32 v49, 0xffff0000, v76
	v_fmac_f32_e32 v42, v43, v49
	v_cvt_pk_bf16_f32 v48, v48, v42
	v_lshlrev_b32_e32 v42, 16, v81
	v_lshlrev_b32_e32 v43, 16, v77
	v_fmac_f32_e32 v42, v44, v43
	v_and_b32_e32 v43, 0xffff0000, v81
	v_and_b32_e32 v44, 0xffff0000, v77
	v_fmac_f32_e32 v43, v45, v44
	v_cvt_pk_bf16_f32 v49, v42, v43
	s_cbranch_vccnz .Lmy_gf_2
	s_waitcnt vmcnt(6)
	s_branch .Lmy_gd_2

; __device__ __forceinline__ unsigned cvt_pk_bf16(float lo, float hi) { unsigned r; asm volatile("v_cvt_pk_bf16_f32 %0, %1, %2" : "=v"(r) : "v"(lo), "v"(hi)); return r; }
; __device__ __forceinline__ float bf_lo(unsigned w) { return __uint_as_float(w << 16); }
; __device__ __forceinline__ float bf_hi(unsigned w) { return __uint_as_float(w & 0xffff0000u); }
; #define EG_LOAD(slot, it) do { const size_t row_ = (size_t)(row0 + ((it) >> 2) * HALF + ((it) & 3) * 16); _Pragma("unroll") for (int bj = 0; bj < 2; ++bj) { \
;             g[slot][bj] = gld((const u32x4*)(G + row_ * ldg + col0 + bj * HALF)); o[slot][bj] = (u32x4){0u, 0u, 0u, 0u}; if (!first) o[slot][bj] = gld((const u32x4*)(MIX + row_ * ldm + col0 + bj * HALF)); } } while (0)
;     __device__ __forceinline__ void operator()(const f32x4 (&acc)[2][2][4][2], const Unit& u, int wr, int wc, int fr, int fq) const {
;     ...
;         EG_LOAD(0, 0);
; #pragma unroll
;         for (int it = 0; it < 8; ++it) { const int ai = it >> 2, m = it & 3, sl = it & 1; const size_t row = (size_t)(row0 + ai * HALF + m * 16);
;             if (it + 1 < 8) EG_LOAD(sl ^ 1, it + 1);
; #pragma unroll
;             for (int bj = 0; bj < 2; ++bj) { const u32x4 gg = g[sl][bj], oo = o[sl][bj]; const f32x4 v0 = acc[ai][bj][m][0], v1 = acc[ai][bj][m][1]; u32x4 w;
;                 w.x = cvt_pk_bf16(bf_lo(oo.x) + bf_lo(gg.x) * v0[0], bf_hi(oo.x) + bf_hi(gg.x) * v0[1]);
;                 w.y = cvt_pk_bf16(bf_lo(oo.y) + bf_lo(gg.y) * v0[2], bf_hi(oo.y) + bf_hi(gg.y) * v0[3]);
;                 w.z = cvt_pk_bf16(bf_lo(oo.z) + bf_lo(gg.z) * v1[0], bf_hi(oo.z) + bf_hi(gg.z) * v1[1]);
;                 w.w = cvt_pk_bf16(bf_lo(oo.w) + bf_lo(gg.w) * v1[2], bf_hi(oo.w) + bf_hi(gg.w) * v1[3]);
;                 gst((u32x4*)(MIX + row * ldm + col0 + bj * HALF), w); }
.Lmy_gd_2:
	v_lshlrev_b32_e32 v42, 16, v66
	v_lshlrev_b32_e32 v43, 16, v70
	v_fmac_f32_e32 v42, v38, v43
	v_and_b32_e32 v38, 0xffff0000, v66
	v_and_b32_e32 v43, 0xffff0000, v70
	v_fmac_f32_e32 v38, v39, v43
	global_store_dwordx4 v[98:99], v[46:49], off
	v_cvt_pk_bf16_f32 v38, v42, v38
	v_lshlrev_b32_e32 v39, 16, v67
	v_lshlrev_b32_e32 v42, 16, v71
	v_fmac_f32_e32 v39, v40, v42
	v_and_b32_e32 v40, 0xffff0000, v67
	v_and_b32_e32 v42, 0xffff0000, v71
	v_fmac_f32_e32 v40, v41, v42
	v_cvt_pk_bf16_f32 v39, v39, v40
	v_lshlrev_b32_e32 v40, 16, v68
	v_lshlrev_b32_e32 v41, 16, v72
	v_fmac_f32_e32 v40, v34, v41
	v_and_b32_e32 v34, 0xffff0000, v68
	v_and_b32_e32 v41, 0xffff0000, v72
	v_fmac_f32_e32 v34, v35, v41
	v_cvt_pk_bf16_f32 v40, v40, v34
	v_lshlrev_b32_e32 v34, 16, v69
	v_lshlrev_b32_e32 v35, 16, v73
	v_fmac_f32_e32 v34, v36, v35
	v_and_b32_e32 v35, 0xffff0000, v69
	v_and_b32_e32 v36, 0xffff0000, v73
	v_fmac_f32_e32 v35, v37, v36
	v_cvt_pk_bf16_f32 v41, v34, v35
	v_or_b32_e32 v34, 48, v114
	v_mov_b64_e32 v[36:37], s[18:19]
	global_store_dwordx4 v[98:99], v[38:41], off offset:256
	v_mad_i64_i32 v[36:37], s[50:51], v34, s81, v[36:37]
	v_lshl_add_u64 v[36:37], v[36:37], 0, v[172:173]
	global_load_dwordx4 v[42:45], v[36:37], off
	v_ashrrev_i32_e32 v35, 31, v34
	v_lshlrev_b64 v[34:35], 11, v[34:35]
	v_lshl_add_u64 v[34:35], s[12:13], 0, v[34:35]
	v_lshl_add_u64 v[66:67], v[34:35], 0, v[172:173]
	v_mov_b32_e32 v34, 0
	s_and_b64 vcc, exec, s[42:43]
	v_mov_b32_e32 v46, 0
	v_mov_b32_e32 v47, 0
	v_mov_b32_e32 v48, 0
	v_mov_b32_e32 v49, 0
	s_cbranch_vccnz .LBB0_1397
	global_load_dwordx4 v[46:49], v[66:67], off

; __device__ __forceinline__ unsigned cvt_pk_bf16(float lo, float hi) { unsigned r; asm volatile("v_cvt_pk_bf16_f32 %0, %1, %2" : "=v"(r) : "v"(lo), "v"(hi)); return r; }
; __device__ __forceinline__ float bf_lo(unsigned w) { return __uint_as_float(w << 16); }
; __device__ __forceinline__ float bf_hi(unsigned w) { return __uint_as_float(w & 0xffff0000u); }
; #define EG_LOAD(slot, it) do { const size_t row_ = (size_t)(row0 + ((it) >> 2) * HALF + ((it) & 3) * 16); _Pragma("unroll") for (int bj = 0; bj < 2; ++bj) { \
;             g[slot][bj] = gld((const u32x4*)(G + row_ * ldg + col0 + bj * HALF)); o[slot][bj] = (u32x4){0u, 0u, 0u, 0u}; if (!first) o[slot][bj] = gld((const u32x4*)(MIX + row_ * ldm + col0 + bj * HALF)); } } while (0)
;     __device__ __forceinline__ void operator()(const f32x4 (&acc)[2][2][4][2], const Unit& u, int wr, int wc, int fr, int fq) const {
;     ...
;         for (int it = 0; it < 8; ++it) { const int ai = it >> 2, m = it & 3, sl = it & 1; const size_t row = (size_t)(row0 + ai * HALF + m * 16);
;             if (it + 1 < 8) EG_LOAD(sl ^ 1, it + 1);
; #pragma unroll
;             for (int bj = 0; bj < 2; ++bj) { const u32x4 gg = g[sl][bj], oo = o[sl][bj]; const f32x4 v0 = acc[ai][bj][m][0], v1 = acc[ai][bj][m][1]; u32x4 w;
;                 w.x = cvt_pk_bf16(bf_lo(oo.x) + bf_lo(gg.x) * v0[0], bf_hi(oo.x) + bf_hi(gg.x) * v0[1]);
;                 w.y = cvt_pk_bf16(bf_lo(oo.y) + bf_lo(gg.y) * v0[2], bf_hi(oo.y) + bf_hi(gg.y) * v0[3]);
;                 w.z = cvt_pk_bf16(bf_lo(oo.z) + bf_lo(gg.z) * v1[0], bf_hi(oo.z) + bf_hi(gg.z) * v1[1]);
;                 w.w = cvt_pk_bf16(bf_lo(oo.w) + bf_lo(gg.w) * v1[2], bf_hi(oo.w) + bf_hi(gg.w) * v1[3]);
;                 gst((u32x4*)(MIX + row * ldm + col0 + bj * HALF), w); }
.Lmy_gd_1:
	v_lshlrev_b32_e32 v68, 16, v62
	v_lshlrev_b32_e32 v69, 16, v58
	v_fmac_f32_e32 v68, v30, v69
	v_and_b32_e32 v30, 0xffff0000, v62
	v_and_b32_e32 v58, 0xffff0000, v58
	v_fmac_f32_e32 v30, v31, v58
	v_lshlrev_b32_e32 v31, 16, v63
	v_lshlrev_b32_e32 v58, 16, v59
	v_fmac_f32_e32 v31, v32, v58
	v_and_b32_e32 v32, 0xffff0000, v63
	v_and_b32_e32 v58, 0xffff0000, v59
	v_fmac_f32_e32 v32, v33, v58
	v_cvt_pk_bf16_f32 v30, v68, v30
	v_cvt_pk_bf16_f32 v31, v31, v32
	v_lshlrev_b32_e32 v32, 16, v64
	v_lshlrev_b32_e32 v33, 16, v60
	v_fmac_f32_e32 v32, v26, v33
	v_and_b32_e32 v26, 0xffff0000, v64
	v_and_b32_e32 v33, 0xffff0000, v60
	v_fmac_f32_e32 v26, v27, v33
	v_cvt_pk_bf16_f32 v32, v32, v26
	v_lshlrev_b32_e32 v26, 16, v65
	v_lshlrev_b32_e32 v27, 16, v61
	v_fmac_f32_e32 v26, v28, v27
	v_and_b32_e32 v27, 0xffff0000, v65
	v_and_b32_e32 v28, 0xffff0000, v61
	v_fmac_f32_e32 v27, v29, v28
	v_cvt_pk_bf16_f32 v33, v26, v27
	s_cbranch_vccnz .Lmy_gf_0
	s_waitcnt vmcnt(6)
	s_branch .Lmy_gd_0

; __device__ __forceinline__ unsigned cvt_pk_bf16(float lo, float hi) { unsigned r; asm volatile("v_cvt_pk_bf16_f32 %0, %1, %2" : "=v"(r) : "v"(lo), "v"(hi)); return r; }
; __device__ __forceinline__ float bf_lo(unsigned w) { return __uint_as_float(w << 16); }
; __device__ __forceinline__ float bf_hi(unsigned w) { return __uint_as_float(w & 0xffff0000u); }
; #define EG_LOAD(slot, it) do { const size_t row_ = (size_t)(row0 + ((it) >> 2) * HALF + ((it) & 3) * 16); _Pragma("unroll") for (int bj = 0; bj < 2; ++bj) { \
;             g[slot][bj] = gld((const u32x4*)(G + row_ * ldg + col0 + bj * HALF)); o[slot][bj] = (u32x4){0u, 0u, 0u, 0u}; if (!first) o[slot][bj] = gld((const u32x4*)(MIX + row_ * ldm + col0 + bj * HALF)); } } while (0)
;     __device__ __forceinline__ void operator()(const f32x4 (&acc)[2][2][4][2], const Unit& u, int wr, int wc, int fr, int fq) const {
;     ...
;         for (int it = 0; it < 8; ++it) { const int ai = it >> 2, m = it & 3, sl = it & 1; const size_t row = (size_t)(row0 + ai * HALF + m * 16);
;             if (it + 1 < 8) EG_LOAD(sl ^ 1, it + 1);
; #pragma unroll
;             for (int bj = 0; bj < 2; ++bj) { const u32x4 gg = g[sl][bj], oo = o[sl][bj]; const f32x4 v0 = acc[ai][bj][m][0], v1 = acc[ai][bj][m][1]; u32x4 w;
;                 w.x = cvt_pk_bf16(bf_lo(oo.x) + bf_lo(gg.x) * v0[0], bf_hi(oo.x) + bf_hi(gg.x) * v0[1]);
;                 w.y = cvt_pk_bf16(bf_lo(oo.y) + bf_lo(gg.y) * v0[2], bf_hi(oo.y) + bf_hi(gg.y) * v0[3]);
;                 w.z = cvt_pk_bf16(bf_lo(oo.z) + bf_lo(gg.z) * v1[0], bf_hi(oo.z) + bf_hi(gg.z) * v1[1]);
;                 w.w = cvt_pk_bf16(bf_lo(oo.w) + bf_lo(gg.w) * v1[2], bf_hi(oo.w) + bf_hi(gg.w) * v1[3]);
;                 gst((u32x4*)(MIX + row * ldm + col0 + bj * HALF), w); }
;             asm volatile("" ::: "memory"); }
; template <class Epi, bool ALIGN_EPI>
; __device__ __forceinline__ void gemm_phase(LAS unsigned char* lds, const Gemm g, const StaticOrder& S, const Epi& E) {
;     ...
;         if (!has_next) break;
; #pragma unroll
;         for (int a = 0; a < 2; ++a)
; #pragma unroll
;             for (int b = 0; b < 2; ++b)
; #pragma unroll
;                 for (int m = 0; m < 4; ++m)
; #pragma unroll
;                     for (int n = 0; n < 2; ++n) acc[a][b][m][n] = (f32x4){0.f, 0.f, 0.f, 0.f};
;         cur = nxt; cA = nA; cB = nB; ++ui;
;         if constexpr (ALIGN_EPI) { if (wr == 1) PG8_BAR; }
.Lmy_gd_0:
	v_lshlrev_b32_e32 v26, 16, v50
	v_lshlrev_b32_e32 v27, 16, v54
	v_fmac_f32_e32 v26, v22, v27
	v_and_b32_e32 v22, 0xffff0000, v50
	v_and_b32_e32 v27, 0xffff0000, v54
	v_fmac_f32_e32 v22, v23, v27
	global_store_dwordx4 v[82:83], v[30:33], off
	v_cvt_pk_bf16_f32 v22, v26, v22
	v_lshlrev_b32_e32 v23, 16, v51
	v_lshlrev_b32_e32 v26, 16, v55
	v_fmac_f32_e32 v23, v24, v26
	v_and_b32_e32 v24, 0xffff0000, v51
	v_and_b32_e32 v26, 0xffff0000, v55
	v_fmac_f32_e32 v24, v25, v26
	v_cvt_pk_bf16_f32 v23, v23, v24
	v_lshlrev_b32_e32 v24, 16, v52
	v_lshlrev_b32_e32 v25, 16, v56
	v_fmac_f32_e32 v24, v14, v25
	v_and_b32_e32 v14, 0xffff0000, v52
	v_and_b32_e32 v25, 0xffff0000, v56
	v_fmac_f32_e32 v14, v15, v25
	v_cvt_pk_bf16_f32 v24, v24, v14
	v_lshlrev_b32_e32 v14, 16, v53
	v_lshlrev_b32_e32 v15, 16, v57
	v_fmac_f32_e32 v14, v16, v15
	v_and_b32_e32 v15, 0xffff0000, v53
	v_and_b32_e32 v16, 0xffff0000, v57
	v_fmac_f32_e32 v15, v17, v16
	v_cvt_pk_bf16_f32 v25, v14, v15
	s_waitcnt vmcnt(2)
	v_lshlrev_b32_e32 v14, 16, v46
	v_lshlrev_b32_e32 v15, 16, v42
	v_fmac_f32_e32 v14, v18, v15
	v_and_b32_e32 v15, 0xffff0000, v46
	v_and_b32_e32 v16, 0xffff0000, v42
	global_store_dwordx4 v[82:83], v[22:25], off offset:256
	v_fmac_f32_e32 v15, v19, v16
	v_cvt_pk_bf16_f32 v14, v14, v15
	v_lshlrev_b32_e32 v15, 16, v47
	v_lshlrev_b32_e32 v16, 16, v43
	v_fmac_f32_e32 v15, v20, v16
	v_and_b32_e32 v16, 0xffff0000, v47
	v_and_b32_e32 v17, 0xffff0000, v43
	v_fmac_f32_e32 v16, v21, v17
	v_cvt_pk_bf16_f32 v15, v15, v16
	v_lshlrev_b32_e32 v16, 16, v48
	v_lshlrev_b32_e32 v17, 16, v44
	v_fmac_f32_e32 v16, v10, v17
	v_and_b32_e32 v10, 0xffff0000, v48
	v_and_b32_e32 v17, 0xffff0000, v44
	v_fmac_f32_e32 v10, v11, v17
	v_cvt_pk_bf16_f32 v16, v16, v10
	v_lshlrev_b32_e32 v10, 16, v49
	v_lshlrev_b32_e32 v11, 16, v45
	v_fmac_f32_e32 v10, v12, v11
	v_and_b32_e32 v11, 0xffff0000, v49
	v_and_b32_e32 v12, 0xffff0000, v45
	v_fmac_f32_e32 v11, v13, v12
	v_cvt_pk_bf16_f32 v17, v10, v11
	s_waitcnt vmcnt(2)
	v_lshlrev_b32_e32 v10, 16, v34
	v_lshlrev_b32_e32 v11, 16, v38
	v_fmac_f32_e32 v10, v6, v11
	v_and_b32_e32 v6, 0xffff0000, v34
	v_and_b32_e32 v11, 0xffff0000, v38
	v_fmac_f32_e32 v6, v7, v11
	global_store_dwordx4 v[66:67], v[14:17], off
	v_cvt_pk_bf16_f32 v6, v10, v6
	v_lshlrev_b32_e32 v7, 16, v35
	v_lshlrev_b32_e32 v10, 16, v39
	v_fmac_f32_e32 v7, v8, v10
	v_and_b32_e32 v8, 0xffff0000, v35
	v_and_b32_e32 v10, 0xffff0000, v39
	v_fmac_f32_e32 v8, v9, v10
	v_cvt_pk_bf16_f32 v7, v7, v8
	v_lshlrev_b32_e32 v8, 16, v36
	v_lshlrev_b32_e32 v9, 16, v40
	v_fmac_f32_e32 v8, v0, v9
	v_and_b32_e32 v0, 0xffff0000, v36
	v_and_b32_e32 v9, 0xffff0000, v40
	v_fmac_f32_e32 v0, v1, v9
	v_cvt_pk_bf16_f32 v8, v8, v0
	v_lshlrev_b32_e32 v0, 16, v37
	v_lshlrev_b32_e32 v1, 16, v41
	v_fmac_f32_e32 v0, v2, v1
	v_and_b32_e32 v1, 0xffff0000, v37
	v_and_b32_e32 v2, 0xffff0000, v41
	v_fmac_f32_e32 v1, v3, v2
	v_cvt_pk_bf16_f32 v9, v0, v1
	global_store_dwordx4 v[66:67], v[6:9], off offset:256
	s_andn2_b64 vcc, exec, s[40:41]
	s_mov_b64 s[40:41], -1
	s_cbranch_vccnz .LBB0_1356
	s_andn2_b64 vcc, exec, s[16:17]
	s_cbranch_vccnz .LBB0_1355
	s_barrier
	s_branch .LBB0_1355
